# P8 sample unit: first five K row groups requested before the wait for the q loads (q round trip hidden)
# speedup vs baseline: 1.0085x; 1.0085x over previous
.LBB0_1028:
	s_lshl_b32 s14, s36, 8
	s_and_b32 s24, s36, -4
	s_and_b32 s37, s14, 0x300
	s_add_i32 s22, s24, 0x4000
	s_lshl_b32 s14, s37, 1
	s_ashr_i32 s23, s22, 31
	s_ashr_i32 s25, s24, 31
	v_lshl_add_u64 v[0:1], v[138:139], 0, s[14:15]
	s_lshl_b64 s[26:27], s[22:23], 11
	s_lshl_b64 s[24:25], s[24:25], 11
	v_lshl_add_u64 v[2:3], v[0:1], 0, s[26:27]
	v_lshl_add_u64 v[0:1], v[0:1], 0, s[24:25]
	v_add_co_u32_e32 v10, vcc, s31, v0
	v_lshl_add_u64 v[12:13], v[0:1], 0, s[16:17]
	s_nop 0
	v_addc_co_u32_e32 v11, vcc, 0, v1, vcc
	v_add_co_u32_e32 v18, vcc, s34, v0
	v_lshl_add_u64 v[22:23], v[0:1], 0, s[18:19]
	s_nop 0
	v_addc_co_u32_e32 v19, vcc, 0, v1, vcc
	v_lshl_add_u64 v[0:1], v[0:1], 0, s[20:21]
	global_load_dwordx2 v[4:5], v[2:3], off
	global_load_dwordx2 v[6:7], v[2:3], off offset:128
	global_load_dwordx2 v[8:9], v[2:3], off offset:256
	s_ashr_i32 s24, s36, 2
	global_load_dwordx2 v[10:11], v[10:11], off offset:2048
	s_lshl_b32 s14, s3, 2
	global_load_dwordx2 v[2:3], v[2:3], off offset:384
	s_nop 0
	global_load_dwordx2 v[14:15], v[12:13], off offset:128
	global_load_dwordx2 v[16:17], v[12:13], off offset:256
	s_nop 0
	global_load_dwordx2 v[12:13], v[12:13], off offset:384
	s_ashr_i32 s25, s24, 31
	global_load_dwordx2 v[20:21], v[18:19], off
	global_load_dwordx2 v[62:63], v[22:23], off offset:128
	global_load_dwordx2 v[66:67], v[22:23], off offset:256
	s_nop 0
	global_load_dwordx2 v[22:23], v[22:23], off offset:384
	s_nop 0
	global_load_dwordx2 v[18:19], v[18:19], off offset:2048
	s_nop 0
	global_load_dwordx2 v[78:79], v[0:1], off offset:128
	global_load_dwordx2 v[82:83], v[0:1], off offset:256
	s_nop 0
	global_load_dwordx2 v[0:1], v[0:1], off offset:384
	s_and_b32 s14, s14, 0xc00
	s_lshl_b64 s[24:25], s[24:25], 20
	s_or_b32 s26, s24, s14
	s_mov_b32 s27, s25
	v_mov_b32_e32 v88, v203
	v_lshl_add_u64 v[94:95], v[142:143], 0, s[26:27]
	s_mov_b32 s32, 0x4000
	s_mov_b32 s33, 0
	global_load_dwordx4 v[96:99], v[94:95], off nt
	global_load_dwordx4 v[100:103], v[94:95], off offset:256 nt
	global_load_dwordx4 v[104:107], v[94:95], off offset:512 nt
	global_load_dwordx4 v[108:111], v[94:95], off offset:768 nt
	v_lshl_add_u64 v[94:95], v[94:95], 0, s[32:33]
	global_load_dwordx4 v[112:115], v[94:95], off nt
	global_load_dwordx4 v[116:119], v[94:95], off offset:256 nt
	global_load_dwordx4 v[120:123], v[94:95], off offset:512 nt
	global_load_dwordx4 v[124:127], v[94:95], off offset:768 nt
	v_lshl_add_u64 v[94:95], v[94:95], 0, s[32:33]
	global_load_dwordx4 v[208:211], v[94:95], off nt
	global_load_dwordx4 v[212:215], v[94:95], off offset:256 nt
	global_load_dwordx4 v[216:219], v[94:95], off offset:512 nt
	global_load_dwordx4 v[220:223], v[94:95], off offset:768 nt
	v_lshl_add_u64 v[94:95], v[94:95], 0, s[32:33]
	global_load_dwordx4 v[224:227], v[94:95], off nt
	global_load_dwordx4 v[228:231], v[94:95], off offset:256 nt
	global_load_dwordx4 v[232:235], v[94:95], off offset:512 nt
	global_load_dwordx4 v[236:239], v[94:95], off offset:768 nt
	v_lshl_add_u64 v[94:95], v[94:95], 0, s[32:33]
	global_load_dwordx4 v[240:243], v[94:95], off nt
	global_load_dwordx4 v[244:247], v[94:95], off offset:256 nt
	global_load_dwordx4 v[248:251], v[94:95], off offset:512 nt
	global_load_dwordx4 v[128:131], v[94:95], off offset:768 nt
	v_lshl_add_u64 v[94:95], v[94:95], 0, s[32:33]
	s_waitcnt vmcnt(20)
	s_barrier
	v_lshlrev_b32_e32 v24, 16, v4
	v_and_b32_e32 v25, 0xffff0000, v4
	v_lshlrev_b32_e32 v26, 16, v5
	v_and_b32_e32 v27, 0xffff0000, v5
	v_lshlrev_b32_e32 v28, 16, v6
	v_and_b32_e32 v29, 0xffff0000, v6
	v_lshlrev_b32_e32 v30, 16, v7
	v_and_b32_e32 v31, 0xffff0000, v7
	v_lshlrev_b32_e32 v32, 16, v8
	v_and_b32_e32 v33, 0xffff0000, v8
	v_lshlrev_b32_e32 v34, 16, v9
	v_and_b32_e32 v35, 0xffff0000, v9
	v_lshlrev_b32_e32 v36, 16, v2
	v_and_b32_e32 v37, 0xffff0000, v2
	v_lshlrev_b32_e32 v38, 16, v3
	v_and_b32_e32 v39, 0xffff0000, v3
	v_lshlrev_b32_e32 v40, 16, v10
	v_and_b32_e32 v41, 0xffff0000, v10
	v_lshlrev_b32_e32 v42, 16, v11
	v_and_b32_e32 v43, 0xffff0000, v11
	v_lshlrev_b32_e32 v44, 16, v14
	v_and_b32_e32 v45, 0xffff0000, v14
	v_lshlrev_b32_e32 v46, 16, v15
	v_and_b32_e32 v47, 0xffff0000, v15
	v_lshlrev_b32_e32 v48, 16, v16
	v_and_b32_e32 v49, 0xffff0000, v16
	v_lshlrev_b32_e32 v50, 16, v17
	v_and_b32_e32 v51, 0xffff0000, v17
	v_lshlrev_b32_e32 v52, 16, v12
	v_and_b32_e32 v53, 0xffff0000, v12
	v_lshlrev_b32_e32 v54, 16, v13
	v_and_b32_e32 v55, 0xffff0000, v13
	v_lshlrev_b32_e32 v56, 16, v20
	v_and_b32_e32 v57, 0xffff0000, v20
	v_lshlrev_b32_e32 v58, 16, v21
	v_and_b32_e32 v59, 0xffff0000, v21
	v_lshlrev_b32_e32 v60, 16, v62
	v_and_b32_e32 v61, 0xffff0000, v62
	v_lshlrev_b32_e32 v62, 16, v63
	v_and_b32_e32 v63, 0xffff0000, v63
	v_lshlrev_b32_e32 v64, 16, v66
	v_and_b32_e32 v65, 0xffff0000, v66
	v_lshlrev_b32_e32 v66, 16, v67
	v_and_b32_e32 v67, 0xffff0000, v67
	v_lshlrev_b32_e32 v68, 16, v22
	v_and_b32_e32 v69, 0xffff0000, v22
	v_lshlrev_b32_e32 v70, 16, v23
	v_and_b32_e32 v71, 0xffff0000, v23
	v_lshlrev_b32_e32 v72, 16, v18
	v_and_b32_e32 v73, 0xffff0000, v18
	v_lshlrev_b32_e32 v74, 16, v19
	v_and_b32_e32 v75, 0xffff0000, v19
	v_lshlrev_b32_e32 v76, 16, v78
	v_and_b32_e32 v77, 0xffff0000, v78
	v_lshlrev_b32_e32 v78, 16, v79
	v_and_b32_e32 v79, 0xffff0000, v79
	v_lshlrev_b32_e32 v80, 16, v82
	v_and_b32_e32 v81, 0xffff0000, v82
	v_lshlrev_b32_e32 v82, 16, v83
	v_and_b32_e32 v83, 0xffff0000, v83
	v_lshlrev_b32_e32 v84, 16, v0
	v_and_b32_e32 v85, 0xffff0000, v0
	v_lshlrev_b32_e32 v86, 16, v1
	v_and_b32_e32 v87, 0xffff0000, v1
	global_load_dwordx4 v[0:3], v[94:95], off nt
	global_load_dwordx4 v[4:7], v[94:95], off offset:256 nt
	global_load_dwordx4 v[8:11], v[94:95], off offset:512 nt
	global_load_dwordx4 v[12:15], v[94:95], off offset:768 nt
	v_lshl_add_u64 v[94:95], v[94:95], 0, s[32:33]
	s_waitcnt vmcnt(20)
	v_mul_f32_e32 v89, v97, v25
	v_fmac_f32_e32 v89, v96, v24
	v_fmac_f32_e32 v89, v98, v26
	v_fmac_f32_e32 v89, v99, v27
	v_mul_f32_e32 v93, v101, v29
	v_fmac_f32_e32 v93, v100, v28
	v_fmac_f32_e32 v93, v102, v30
	v_fmac_f32_e32 v93, v103, v31
	v_add_f32_e32 v89, v89, v93
	v_mul_f32_e32 v93, v105, v33
	v_fmac_f32_e32 v93, v104, v32
	v_fmac_f32_e32 v93, v106, v34
	v_fmac_f32_e32 v93, v107, v35
	v_add_f32_e32 v89, v89, v93
	v_mul_f32_e32 v93, v109, v37
	v_fmac_f32_e32 v93, v108, v36
	v_fmac_f32_e32 v93, v110, v38
	v_fmac_f32_e32 v93, v111, v39
	v_add_f32_e32 v89, v89, v93
	v_mul_f32_e32 v90, v97, v41
	v_fmac_f32_e32 v90, v96, v40
	v_fmac_f32_e32 v90, v98, v42
	v_fmac_f32_e32 v90, v99, v43
	v_mul_f32_e32 v93, v101, v45
	v_fmac_f32_e32 v93, v100, v44
	v_fmac_f32_e32 v93, v102, v46
	v_fmac_f32_e32 v93, v103, v47
	v_add_f32_e32 v90, v90, v93
	v_mul_f32_e32 v93, v105, v49
	v_fmac_f32_e32 v93, v104, v48
	v_fmac_f32_e32 v93, v106, v50
	v_fmac_f32_e32 v93, v107, v51
	v_add_f32_e32 v90, v90, v93
	v_mul_f32_e32 v93, v109, v53
	v_fmac_f32_e32 v93, v108, v52
	v_fmac_f32_e32 v93, v110, v54
	v_fmac_f32_e32 v93, v111, v55
	v_add_f32_e32 v90, v90, v93
	v_mul_f32_e32 v91, v97, v57
	v_fmac_f32_e32 v91, v96, v56
	v_fmac_f32_e32 v91, v98, v58
	v_fmac_f32_e32 v91, v99, v59
	v_mul_f32_e32 v93, v101, v61
	v_fmac_f32_e32 v93, v100, v60
	v_fmac_f32_e32 v93, v102, v62
	v_fmac_f32_e32 v93, v103, v63
	v_add_f32_e32 v91, v91, v93
	v_mul_f32_e32 v93, v105, v65
	v_fmac_f32_e32 v93, v104, v64
	v_fmac_f32_e32 v93, v106, v66
	v_fmac_f32_e32 v93, v107, v67
	v_add_f32_e32 v91, v91, v93
	v_mul_f32_e32 v93, v109, v69
	v_fmac_f32_e32 v93, v108, v68
	v_fmac_f32_e32 v93, v110, v70
	v_fmac_f32_e32 v93, v111, v71
	v_add_f32_e32 v91, v91, v93
	v_mul_f32_e32 v92, v97, v73
	v_fmac_f32_e32 v92, v96, v72
	v_fmac_f32_e32 v92, v98, v74
	v_fmac_f32_e32 v92, v99, v75
	v_mul_f32_e32 v93, v101, v77
	v_fmac_f32_e32 v93, v100, v76
	v_fmac_f32_e32 v93, v102, v78
	v_fmac_f32_e32 v93, v103, v79
	v_add_f32_e32 v92, v92, v93
	v_mul_f32_e32 v93, v105, v81
	v_fmac_f32_e32 v93, v104, v80
	v_fmac_f32_e32 v93, v106, v82
	v_fmac_f32_e32 v93, v107, v83
	v_add_f32_e32 v92, v92, v93
	v_mul_f32_e32 v93, v109, v85
	v_fmac_f32_e32 v93, v108, v84
	v_fmac_f32_e32 v93, v110, v86
	v_fmac_f32_e32 v93, v111, v87
	v_add_f32_e32 v92, v92, v93
	global_load_dwordx4 v[96:99], v[94:95], off nt
	global_load_dwordx4 v[100:103], v[94:95], off offset:256 nt
	global_load_dwordx4 v[104:107], v[94:95], off offset:512 nt
	global_load_dwordx4 v[108:111], v[94:95], off offset:768 nt
	v_lshl_add_u64 v[94:95], v[94:95], 0, s[32:33]
	v_add_f32_dpp v89, v89, v89 quad_perm:[1,0,3,2] row_mask:0xf bank_mask:0xf
	v_add_f32_dpp v90, v90, v90 quad_perm:[1,0,3,2] row_mask:0xf bank_mask:0xf
	v_add_f32_dpp v91, v91, v91 quad_perm:[1,0,3,2] row_mask:0xf bank_mask:0xf
	v_add_f32_dpp v92, v92, v92 quad_perm:[1,0,3,2] row_mask:0xf bank_mask:0xf
	v_add_f32_dpp v89, v89, v89 quad_perm:[2,3,0,1] row_mask:0xf bank_mask:0xf
	v_add_f32_dpp v90, v90, v90 quad_perm:[2,3,0,1] row_mask:0xf bank_mask:0xf
	v_add_f32_dpp v91, v91, v91 quad_perm:[2,3,0,1] row_mask:0xf bank_mask:0xf
	v_add_f32_dpp v92, v92, v92 quad_perm:[2,3,0,1] row_mask:0xf bank_mask:0xf
	v_add_f32_dpp v89, v89, v89 row_half_mirror row_mask:0xf bank_mask:0xf
	v_add_f32_dpp v90, v90, v90 row_half_mirror row_mask:0xf bank_mask:0xf
	v_add_f32_dpp v91, v91, v91 row_half_mirror row_mask:0xf bank_mask:0xf
	v_add_f32_dpp v92, v92, v92 row_half_mirror row_mask:0xf bank_mask:0xf
	v_add_f32_dpp v89, v89, v89 row_mirror row_mask:0xf bank_mask:0xf
	v_add_f32_dpp v90, v90, v90 row_mirror row_mask:0xf bank_mask:0xf
	v_add_f32_dpp v91, v91, v91 row_mirror row_mask:0xf bank_mask:0xf
	v_add_f32_dpp v92, v92, v92 row_mirror row_mask:0xf bank_mask:0xf
	v_mul_f32_e32 v89, 0x3d800000, v89
	v_mul_f32_e32 v90, 0x3d800000, v90
	v_mul_f32_e32 v91, 0x3d800000, v91
	v_mul_f32_e32 v92, 0x3d800000, v92
	s_and_saveexec_b64 s[28:29], s[0:1]
	ds_write_b32 v88, v89
	ds_write_b32 v88, v90 offset:1024
	ds_write_b32 v88, v91 offset:2048
	ds_write_b32 v88, v92 offset:3072
	s_mov_b64 exec, s[28:29]
	s_waitcnt vmcnt(20)
	v_mul_f32_e32 v89, v113, v25
	v_fmac_f32_e32 v89, v112, v24
	v_fmac_f32_e32 v89, v114, v26
	v_fmac_f32_e32 v89, v115, v27
	v_mul_f32_e32 v93, v117, v29
	v_fmac_f32_e32 v93, v116, v28
	v_fmac_f32_e32 v93, v118, v30
	v_fmac_f32_e32 v93, v119, v31
	v_add_f32_e32 v89, v89, v93
	v_mul_f32_e32 v93, v121, v33
	v_fmac_f32_e32 v93, v120, v32
	v_fmac_f32_e32 v93, v122, v34
	v_fmac_f32_e32 v93, v123, v35
	v_add_f32_e32 v89, v89, v93
	v_mul_f32_e32 v93, v125, v37
	v_fmac_f32_e32 v93, v124, v36
	v_fmac_f32_e32 v93, v126, v38
	v_fmac_f32_e32 v93, v127, v39
	v_add_f32_e32 v89, v89, v93
	v_mul_f32_e32 v90, v113, v41
	v_fmac_f32_e32 v90, v112, v40
	v_fmac_f32_e32 v90, v114, v42
	v_fmac_f32_e32 v90, v115, v43
	v_mul_f32_e32 v93, v117, v45
	v_fmac_f32_e32 v93, v116, v44
	v_fmac_f32_e32 v93, v118, v46
	v_fmac_f32_e32 v93, v119, v47
	v_add_f32_e32 v90, v90, v93
	v_mul_f32_e32 v93, v121, v49
	v_fmac_f32_e32 v93, v120, v48
	v_fmac_f32_e32 v93, v122, v50
	v_fmac_f32_e32 v93, v123, v51
	v_add_f32_e32 v90, v90, v93
	v_mul_f32_e32 v93, v125, v53
	v_fmac_f32_e32 v93, v124, v52
	v_fmac_f32_e32 v93, v126, v54
	v_fmac_f32_e32 v93, v127, v55
	v_add_f32_e32 v90, v90, v93
	v_mul_f32_e32 v91, v113, v57
	v_fmac_f32_e32 v91, v112, v56
	v_fmac_f32_e32 v91, v114, v58
	v_fmac_f32_e32 v91, v115, v59
	v_mul_f32_e32 v93, v117, v61
	v_fmac_f32_e32 v93, v116, v60
	v_fmac_f32_e32 v93, v118, v62
	v_fmac_f32_e32 v93, v119, v63
	v_add_f32_e32 v91, v91, v93
	v_mul_f32_e32 v93, v121, v65
	v_fmac_f32_e32 v93, v120, v64
	v_fmac_f32_e32 v93, v122, v66
	v_fmac_f32_e32 v93, v123, v67
	v_add_f32_e32 v91, v91, v93
	v_mul_f32_e32 v93, v125, v69
	v_fmac_f32_e32 v93, v124, v68
	v_fmac_f32_e32 v93, v126, v70
	v_fmac_f32_e32 v93, v127, v71
	v_add_f32_e32 v91, v91, v93
	v_mul_f32_e32 v92, v113, v73
	v_fmac_f32_e32 v92, v112, v72
	v_fmac_f32_e32 v92, v114, v74
	v_fmac_f32_e32 v92, v115, v75
	v_mul_f32_e32 v93, v117, v77
	v_fmac_f32_e32 v93, v116, v76
	v_fmac_f32_e32 v93, v118, v78
	v_fmac_f32_e32 v93, v119, v79
	v_add_f32_e32 v92, v92, v93
	v_mul_f32_e32 v93, v121, v81
	v_fmac_f32_e32 v93, v120, v80
	v_fmac_f32_e32 v93, v122, v82
	v_fmac_f32_e32 v93, v123, v83
	v_add_f32_e32 v92, v92, v93
	v_mul_f32_e32 v93, v125, v85
	v_fmac_f32_e32 v93, v124, v84
	v_fmac_f32_e32 v93, v126, v86
	v_fmac_f32_e32 v93, v127, v87
	v_add_f32_e32 v92, v92, v93
	global_load_dwordx4 v[112:115], v[94:95], off nt
	global_load_dwordx4 v[116:119], v[94:95], off offset:256 nt
	global_load_dwordx4 v[120:123], v[94:95], off offset:512 nt
	global_load_dwordx4 v[124:127], v[94:95], off offset:768 nt
	v_lshl_add_u64 v[94:95], v[94:95], 0, s[32:33]
	v_add_f32_dpp v89, v89, v89 quad_perm:[1,0,3,2] row_mask:0xf bank_mask:0xf
	v_add_f32_dpp v90, v90, v90 quad_perm:[1,0,3,2] row_mask:0xf bank_mask:0xf
	v_add_f32_dpp v91, v91, v91 quad_perm:[1,0,3,2] row_mask:0xf bank_mask:0xf
	v_add_f32_dpp v92, v92, v92 quad_perm:[1,0,3,2] row_mask:0xf bank_mask:0xf
	v_add_f32_dpp v89, v89, v89 quad_perm:[2,3,0,1] row_mask:0xf bank_mask:0xf
	v_add_f32_dpp v90, v90, v90 quad_perm:[2,3,0,1] row_mask:0xf bank_mask:0xf
	v_add_f32_dpp v91, v91, v91 quad_perm:[2,3,0,1] row_mask:0xf bank_mask:0xf
	v_add_f32_dpp v92, v92, v92 quad_perm:[2,3,0,1] row_mask:0xf bank_mask:0xf
	v_add_f32_dpp v89, v89, v89 row_half_mirror row_mask:0xf bank_mask:0xf
	v_add_f32_dpp v90, v90, v90 row_half_mirror row_mask:0xf bank_mask:0xf
	v_add_f32_dpp v91, v91, v91 row_half_mirror row_mask:0xf bank_mask:0xf
	v_add_f32_dpp v92, v92, v92 row_half_mirror row_mask:0xf bank_mask:0xf
	v_add_f32_dpp v89, v89, v89 row_mirror row_mask:0xf bank_mask:0xf
	v_add_f32_dpp v90, v90, v90 row_mirror row_mask:0xf bank_mask:0xf
	v_add_f32_dpp v91, v91, v91 row_mirror row_mask:0xf bank_mask:0xf
	v_add_f32_dpp v92, v92, v92 row_mirror row_mask:0xf bank_mask:0xf
	v_mul_f32_e32 v89, 0x3d800000, v89
	v_mul_f32_e32 v90, 0x3d800000, v90
	v_mul_f32_e32 v91, 0x3d800000, v91
	v_mul_f32_e32 v92, 0x3d800000, v92
	s_and_saveexec_b64 s[28:29], s[0:1]
	ds_write_b32 v88, v89 offset:16
	ds_write_b32 v88, v90 offset:1040
	ds_write_b32 v88, v91 offset:2064
	ds_write_b32 v88, v92 offset:3088
	s_mov_b64 exec, s[28:29]
	s_waitcnt vmcnt(20)
	v_mul_f32_e32 v89, v209, v25
	v_fmac_f32_e32 v89, v208, v24
	v_fmac_f32_e32 v89, v210, v26
	v_fmac_f32_e32 v89, v211, v27
	v_mul_f32_e32 v93, v213, v29
	v_fmac_f32_e32 v93, v212, v28
	v_fmac_f32_e32 v93, v214, v30
	v_fmac_f32_e32 v93, v215, v31
	v_add_f32_e32 v89, v89, v93
	v_mul_f32_e32 v93, v217, v33
	v_fmac_f32_e32 v93, v216, v32
	v_fmac_f32_e32 v93, v218, v34
	v_fmac_f32_e32 v93, v219, v35
	v_add_f32_e32 v89, v89, v93
	v_mul_f32_e32 v93, v221, v37
	v_fmac_f32_e32 v93, v220, v36
	v_fmac_f32_e32 v93, v222, v38
	v_fmac_f32_e32 v93, v223, v39
	v_add_f32_e32 v89, v89, v93
	v_mul_f32_e32 v90, v209, v41
	v_fmac_f32_e32 v90, v208, v40
	v_fmac_f32_e32 v90, v210, v42
	v_fmac_f32_e32 v90, v211, v43
	v_mul_f32_e32 v93, v213, v45
	v_fmac_f32_e32 v93, v212, v44
	v_fmac_f32_e32 v93, v214, v46
	v_fmac_f32_e32 v93, v215, v47
	v_add_f32_e32 v90, v90, v93
	v_mul_f32_e32 v93, v217, v49
	v_fmac_f32_e32 v93, v216, v48
	v_fmac_f32_e32 v93, v218, v50
	v_fmac_f32_e32 v93, v219, v51
	v_add_f32_e32 v90, v90, v93
	v_mul_f32_e32 v93, v221, v53
	v_fmac_f32_e32 v93, v220, v52
	v_fmac_f32_e32 v93, v222, v54
	v_fmac_f32_e32 v93, v223, v55
	v_add_f32_e32 v90, v90, v93
	v_mul_f32_e32 v91, v209, v57
	v_fmac_f32_e32 v91, v208, v56
	v_fmac_f32_e32 v91, v210, v58
	v_fmac_f32_e32 v91, v211, v59
	v_mul_f32_e32 v93, v213, v61
	v_fmac_f32_e32 v93, v212, v60
	v_fmac_f32_e32 v93, v214, v62
	v_fmac_f32_e32 v93, v215, v63
	v_add_f32_e32 v91, v91, v93
	v_mul_f32_e32 v93, v217, v65
	v_fmac_f32_e32 v93, v216, v64
	v_fmac_f32_e32 v93, v218, v66
	v_fmac_f32_e32 v93, v219, v67
	v_add_f32_e32 v91, v91, v93
	v_mul_f32_e32 v93, v221, v69
	v_fmac_f32_e32 v93, v220, v68
	v_fmac_f32_e32 v93, v222, v70
	v_fmac_f32_e32 v93, v223, v71
	v_add_f32_e32 v91, v91, v93
	v_mul_f32_e32 v92, v209, v73
	v_fmac_f32_e32 v92, v208, v72
	v_fmac_f32_e32 v92, v210, v74
	v_fmac_f32_e32 v92, v211, v75
	v_mul_f32_e32 v93, v213, v77
	v_fmac_f32_e32 v93, v212, v76
	v_fmac_f32_e32 v93, v214, v78
	v_fmac_f32_e32 v93, v215, v79
	v_add_f32_e32 v92, v92, v93
	v_mul_f32_e32 v93, v217, v81
	v_fmac_f32_e32 v93, v216, v80
	v_fmac_f32_e32 v93, v218, v82
	v_fmac_f32_e32 v93, v219, v83
	v_add_f32_e32 v92, v92, v93
	v_mul_f32_e32 v93, v221, v85
	v_fmac_f32_e32 v93, v220, v84
	v_fmac_f32_e32 v93, v222, v86
	v_fmac_f32_e32 v93, v223, v87
	v_add_f32_e32 v92, v92, v93
	v_add_f32_dpp v89, v89, v89 quad_perm:[1,0,3,2] row_mask:0xf bank_mask:0xf
	v_add_f32_dpp v90, v90, v90 quad_perm:[1,0,3,2] row_mask:0xf bank_mask:0xf
	v_add_f32_dpp v91, v91, v91 quad_perm:[1,0,3,2] row_mask:0xf bank_mask:0xf
	v_add_f32_dpp v92, v92, v92 quad_perm:[1,0,3,2] row_mask:0xf bank_mask:0xf
	v_add_f32_dpp v89, v89, v89 quad_perm:[2,3,0,1] row_mask:0xf bank_mask:0xf
	v_add_f32_dpp v90, v90, v90 quad_perm:[2,3,0,1] row_mask:0xf bank_mask:0xf
	v_add_f32_dpp v91, v91, v91 quad_perm:[2,3,0,1] row_mask:0xf bank_mask:0xf
	v_add_f32_dpp v92, v92, v92 quad_perm:[2,3,0,1] row_mask:0xf bank_mask:0xf
	v_add_f32_dpp v89, v89, v89 row_half_mirror row_mask:0xf bank_mask:0xf
	v_add_f32_dpp v90, v90, v90 row_half_mirror row_mask:0xf bank_mask:0xf
	v_add_f32_dpp v91, v91, v91 row_half_mirror row_mask:0xf bank_mask:0xf
	v_add_f32_dpp v92, v92, v92 row_half_mirror row_mask:0xf bank_mask:0xf
	v_add_f32_dpp v89, v89, v89 row_mirror row_mask:0xf bank_mask:0xf
	v_add_f32_dpp v90, v90, v90 row_mirror row_mask:0xf bank_mask:0xf
	v_add_f32_dpp v91, v91, v91 row_mirror row_mask:0xf bank_mask:0xf
	v_add_f32_dpp v92, v92, v92 row_mirror row_mask:0xf bank_mask:0xf
	v_mul_f32_e32 v89, 0x3d800000, v89
	v_mul_f32_e32 v90, 0x3d800000, v90
	v_mul_f32_e32 v91, 0x3d800000, v91
	v_mul_f32_e32 v92, 0x3d800000, v92
	s_and_saveexec_b64 s[28:29], s[0:1]
	ds_write_b32 v88, v89 offset:32
	ds_write_b32 v88, v90 offset:1056
	ds_write_b32 v88, v91 offset:2080
	ds_write_b32 v88, v92 offset:3104
	s_mov_b64 exec, s[28:29]
	s_waitcnt vmcnt(16)
	v_mul_f32_e32 v89, v225, v25
	v_fmac_f32_e32 v89, v224, v24
	v_fmac_f32_e32 v89, v226, v26
	v_fmac_f32_e32 v89, v227, v27
	v_mul_f32_e32 v93, v229, v29
	v_fmac_f32_e32 v93, v228, v28
	v_fmac_f32_e32 v93, v230, v30
	v_fmac_f32_e32 v93, v231, v31
	v_add_f32_e32 v89, v89, v93
	v_mul_f32_e32 v93, v233, v33
	v_fmac_f32_e32 v93, v232, v32
	v_fmac_f32_e32 v93, v234, v34
	v_fmac_f32_e32 v93, v235, v35
	v_add_f32_e32 v89, v89, v93
	v_mul_f32_e32 v93, v237, v37
	v_fmac_f32_e32 v93, v236, v36
	v_fmac_f32_e32 v93, v238, v38
	v_fmac_f32_e32 v93, v239, v39
	v_add_f32_e32 v89, v89, v93
	v_mul_f32_e32 v90, v225, v41
	v_fmac_f32_e32 v90, v224, v40
	v_fmac_f32_e32 v90, v226, v42
	v_fmac_f32_e32 v90, v227, v43
	v_mul_f32_e32 v93, v229, v45
	v_fmac_f32_e32 v93, v228, v44
	v_fmac_f32_e32 v93, v230, v46
	v_fmac_f32_e32 v93, v231, v47
	v_add_f32_e32 v90, v90, v93
	v_mul_f32_e32 v93, v233, v49
	v_fmac_f32_e32 v93, v232, v48
	v_fmac_f32_e32 v93, v234, v50
	v_fmac_f32_e32 v93, v235, v51
	v_add_f32_e32 v90, v90, v93
	v_mul_f32_e32 v93, v237, v53
	v_fmac_f32_e32 v93, v236, v52
	v_fmac_f32_e32 v93, v238, v54
	v_fmac_f32_e32 v93, v239, v55
	v_add_f32_e32 v90, v90, v93
	v_mul_f32_e32 v91, v225, v57
	v_fmac_f32_e32 v91, v224, v56
	v_fmac_f32_e32 v91, v226, v58
	v_fmac_f32_e32 v91, v227, v59
	v_mul_f32_e32 v93, v229, v61
	v_fmac_f32_e32 v93, v228, v60
	v_fmac_f32_e32 v93, v230, v62
	v_fmac_f32_e32 v93, v231, v63
	v_add_f32_e32 v91, v91, v93
	v_mul_f32_e32 v93, v233, v65
	v_fmac_f32_e32 v93, v232, v64
	v_fmac_f32_e32 v93, v234, v66
	v_fmac_f32_e32 v93, v235, v67
	v_add_f32_e32 v91, v91, v93
	v_mul_f32_e32 v93, v237, v69
	v_fmac_f32_e32 v93, v236, v68
	v_fmac_f32_e32 v93, v238, v70
	v_fmac_f32_e32 v93, v239, v71
	v_add_f32_e32 v91, v91, v93
	v_mul_f32_e32 v92, v225, v73
	v_fmac_f32_e32 v92, v224, v72
	v_fmac_f32_e32 v92, v226, v74
	v_fmac_f32_e32 v92, v227, v75
	v_mul_f32_e32 v93, v229, v77
	v_fmac_f32_e32 v93, v228, v76
	v_fmac_f32_e32 v93, v230, v78
	v_fmac_f32_e32 v93, v231, v79
	v_add_f32_e32 v92, v92, v93
	v_mul_f32_e32 v93, v233, v81
	v_fmac_f32_e32 v93, v232, v80
	v_fmac_f32_e32 v93, v234, v82
	v_fmac_f32_e32 v93, v235, v83
	v_add_f32_e32 v92, v92, v93
	v_mul_f32_e32 v93, v237, v85
	v_fmac_f32_e32 v93, v236, v84
	v_fmac_f32_e32 v93, v238, v86
	v_fmac_f32_e32 v93, v239, v87
	v_add_f32_e32 v92, v92, v93
	v_add_f32_dpp v89, v89, v89 quad_perm:[1,0,3,2] row_mask:0xf bank_mask:0xf
	v_add_f32_dpp v90, v90, v90 quad_perm:[1,0,3,2] row_mask:0xf bank_mask:0xf
	v_add_f32_dpp v91, v91, v91 quad_perm:[1,0,3,2] row_mask:0xf bank_mask:0xf
	v_add_f32_dpp v92, v92, v92 quad_perm:[1,0,3,2] row_mask:0xf bank_mask:0xf
	v_add_f32_dpp v89, v89, v89 quad_perm:[2,3,0,1] row_mask:0xf bank_mask:0xf
	v_add_f32_dpp v90, v90, v90 quad_perm:[2,3,0,1] row_mask:0xf bank_mask:0xf
	v_add_f32_dpp v91, v91, v91 quad_perm:[2,3,0,1] row_mask:0xf bank_mask:0xf
	v_add_f32_dpp v92, v92, v92 quad_perm:[2,3,0,1] row_mask:0xf bank_mask:0xf
	v_add_f32_dpp v89, v89, v89 row_half_mirror row_mask:0xf bank_mask:0xf
	v_add_f32_dpp v90, v90, v90 row_half_mirror row_mask:0xf bank_mask:0xf
	v_add_f32_dpp v91, v91, v91 row_half_mirror row_mask:0xf bank_mask:0xf
	v_add_f32_dpp v92, v92, v92 row_half_mirror row_mask:0xf bank_mask:0xf
	v_add_f32_dpp v89, v89, v89 row_mirror row_mask:0xf bank_mask:0xf
	v_add_f32_dpp v90, v90, v90 row_mirror row_mask:0xf bank_mask:0xf
	v_add_f32_dpp v91, v91, v91 row_mirror row_mask:0xf bank_mask:0xf
	v_add_f32_dpp v92, v92, v92 row_mirror row_mask:0xf bank_mask:0xf
	v_mul_f32_e32 v89, 0x3d800000, v89
	v_mul_f32_e32 v90, 0x3d800000, v90
	v_mul_f32_e32 v91, 0x3d800000, v91
	v_mul_f32_e32 v92, 0x3d800000, v92
	s_and_saveexec_b64 s[28:29], s[0:1]
	ds_write_b32 v88, v89 offset:48
	ds_write_b32 v88, v90 offset:1072
	ds_write_b32 v88, v91 offset:2096
	ds_write_b32 v88, v92 offset:3120
	s_mov_b64 exec, s[28:29]
	s_waitcnt vmcnt(12)
	v_mul_f32_e32 v89, v241, v25
	v_fmac_f32_e32 v89, v240, v24
	v_fmac_f32_e32 v89, v242, v26
	v_fmac_f32_e32 v89, v243, v27
	v_mul_f32_e32 v93, v245, v29
	v_fmac_f32_e32 v93, v244, v28
	v_fmac_f32_e32 v93, v246, v30
	v_fmac_f32_e32 v93, v247, v31
	v_add_f32_e32 v89, v89, v93
	v_mul_f32_e32 v93, v249, v33
	v_fmac_f32_e32 v93, v248, v32
	v_fmac_f32_e32 v93, v250, v34
	v_fmac_f32_e32 v93, v251, v35
	v_add_f32_e32 v89, v89, v93
	v_mul_f32_e32 v93, v129, v37
	v_fmac_f32_e32 v93, v128, v36
	v_fmac_f32_e32 v93, v130, v38
	v_fmac_f32_e32 v93, v131, v39
	v_add_f32_e32 v89, v89, v93
	v_mul_f32_e32 v90, v241, v41
	v_fmac_f32_e32 v90, v240, v40
	v_fmac_f32_e32 v90, v242, v42
	v_fmac_f32_e32 v90, v243, v43
	v_mul_f32_e32 v93, v245, v45
	v_fmac_f32_e32 v93, v244, v44
	v_fmac_f32_e32 v93, v246, v46
	v_fmac_f32_e32 v93, v247, v47
	v_add_f32_e32 v90, v90, v93
	v_mul_f32_e32 v93, v249, v49
	v_fmac_f32_e32 v93, v248, v48
	v_fmac_f32_e32 v93, v250, v50
	v_fmac_f32_e32 v93, v251, v51
	v_add_f32_e32 v90, v90, v93
	v_mul_f32_e32 v93, v129, v53
	v_fmac_f32_e32 v93, v128, v52
	v_fmac_f32_e32 v93, v130, v54
	v_fmac_f32_e32 v93, v131, v55
	v_add_f32_e32 v90, v90, v93
	v_mul_f32_e32 v91, v241, v57
	v_fmac_f32_e32 v91, v240, v56
	v_fmac_f32_e32 v91, v242, v58
	v_fmac_f32_e32 v91, v243, v59
	v_mul_f32_e32 v93, v245, v61
	v_fmac_f32_e32 v93, v244, v60
	v_fmac_f32_e32 v93, v246, v62
	v_fmac_f32_e32 v93, v247, v63
	v_add_f32_e32 v91, v91, v93
	v_mul_f32_e32 v93, v249, v65
	v_fmac_f32_e32 v93, v248, v64
	v_fmac_f32_e32 v93, v250, v66
	v_fmac_f32_e32 v93, v251, v67
	v_add_f32_e32 v91, v91, v93
	v_mul_f32_e32 v93, v129, v69
	v_fmac_f32_e32 v93, v128, v68
	v_fmac_f32_e32 v93, v130, v70
	v_fmac_f32_e32 v93, v131, v71
	v_add_f32_e32 v91, v91, v93
	v_mul_f32_e32 v92, v241, v73
	v_fmac_f32_e32 v92, v240, v72
	v_fmac_f32_e32 v92, v242, v74
	v_fmac_f32_e32 v92, v243, v75
	v_mul_f32_e32 v93, v245, v77
	v_fmac_f32_e32 v93, v244, v76
	v_fmac_f32_e32 v93, v246, v78
	v_fmac_f32_e32 v93, v247, v79
	v_add_f32_e32 v92, v92, v93
	v_mul_f32_e32 v93, v249, v81
	v_fmac_f32_e32 v93, v248, v80
	v_fmac_f32_e32 v93, v250, v82
	v_fmac_f32_e32 v93, v251, v83
	v_add_f32_e32 v92, v92, v93
	v_mul_f32_e32 v93, v129, v85
	v_fmac_f32_e32 v93, v128, v84
	v_fmac_f32_e32 v93, v130, v86
	v_fmac_f32_e32 v93, v131, v87
	v_add_f32_e32 v92, v92, v93
	v_add_f32_dpp v89, v89, v89 quad_perm:[1,0,3,2] row_mask:0xf bank_mask:0xf
	v_add_f32_dpp v90, v90, v90 quad_perm:[1,0,3,2] row_mask:0xf bank_mask:0xf
	v_add_f32_dpp v91, v91, v91 quad_perm:[1,0,3,2] row_mask:0xf bank_mask:0xf
	v_add_f32_dpp v92, v92, v92 quad_perm:[1,0,3,2] row_mask:0xf bank_mask:0xf
	v_add_f32_dpp v89, v89, v89 quad_perm:[2,3,0,1] row_mask:0xf bank_mask:0xf
	v_add_f32_dpp v90, v90, v90 quad_perm:[2,3,0,1] row_mask:0xf bank_mask:0xf
	v_add_f32_dpp v91, v91, v91 quad_perm:[2,3,0,1] row_mask:0xf bank_mask:0xf
	v_add_f32_dpp v92, v92, v92 quad_perm:[2,3,0,1] row_mask:0xf bank_mask:0xf
	v_add_f32_dpp v89, v89, v89 row_half_mirror row_mask:0xf bank_mask:0xf
	v_add_f32_dpp v90, v90, v90 row_half_mirror row_mask:0xf bank_mask:0xf
	v_add_f32_dpp v91, v91, v91 row_half_mirror row_mask:0xf bank_mask:0xf
	v_add_f32_dpp v92, v92, v92 row_half_mirror row_mask:0xf bank_mask:0xf
	v_add_f32_dpp v89, v89, v89 row_mirror row_mask:0xf bank_mask:0xf
	v_add_f32_dpp v90, v90, v90 row_mirror row_mask:0xf bank_mask:0xf
	v_add_f32_dpp v91, v91, v91 row_mirror row_mask:0xf bank_mask:0xf
	v_add_f32_dpp v92, v92, v92 row_mirror row_mask:0xf bank_mask:0xf
	v_mul_f32_e32 v89, 0x3d800000, v89
	v_mul_f32_e32 v90, 0x3d800000, v90
	v_mul_f32_e32 v91, 0x3d800000, v91
	v_mul_f32_e32 v92, 0x3d800000, v92
	s_and_saveexec_b64 s[28:29], s[0:1]
	ds_write_b32 v88, v89 offset:64
	ds_write_b32 v88, v90 offset:1088
	ds_write_b32 v88, v91 offset:2112
	ds_write_b32 v88, v92 offset:3136
	s_mov_b64 exec, s[28:29]
	s_waitcnt vmcnt(8)
	v_mul_f32_e32 v89, v1, v25
	v_fmac_f32_e32 v89, v0, v24
	v_fmac_f32_e32 v89, v2, v26
	v_fmac_f32_e32 v89, v3, v27
	v_mul_f32_e32 v93, v5, v29
	v_fmac_f32_e32 v93, v4, v28
	v_fmac_f32_e32 v93, v6, v30
	v_fmac_f32_e32 v93, v7, v31
	v_add_f32_e32 v89, v89, v93
	v_mul_f32_e32 v93, v9, v33
	v_fmac_f32_e32 v93, v8, v32
	v_fmac_f32_e32 v93, v10, v34
	v_fmac_f32_e32 v93, v11, v35
	v_add_f32_e32 v89, v89, v93
	v_mul_f32_e32 v93, v13, v37
	v_fmac_f32_e32 v93, v12, v36
	v_fmac_f32_e32 v93, v14, v38
	v_fmac_f32_e32 v93, v15, v39
	v_add_f32_e32 v89, v89, v93
	v_mul_f32_e32 v90, v1, v41
	v_fmac_f32_e32 v90, v0, v40
	v_fmac_f32_e32 v90, v2, v42
	v_fmac_f32_e32 v90, v3, v43
	v_mul_f32_e32 v93, v5, v45
	v_fmac_f32_e32 v93, v4, v44
	v_fmac_f32_e32 v93, v6, v46
	v_fmac_f32_e32 v93, v7, v47
	v_add_f32_e32 v90, v90, v93
	v_mul_f32_e32 v93, v9, v49
	v_fmac_f32_e32 v93, v8, v48
	v_fmac_f32_e32 v93, v10, v50
	v_fmac_f32_e32 v93, v11, v51
	v_add_f32_e32 v90, v90, v93
	v_mul_f32_e32 v93, v13, v53
	v_fmac_f32_e32 v93, v12, v52
	v_fmac_f32_e32 v93, v14, v54
	v_fmac_f32_e32 v93, v15, v55
	v_add_f32_e32 v90, v90, v93
	v_mul_f32_e32 v91, v1, v57
	v_fmac_f32_e32 v91, v0, v56
	v_fmac_f32_e32 v91, v2, v58
	v_fmac_f32_e32 v91, v3, v59
	v_mul_f32_e32 v93, v5, v61
	v_fmac_f32_e32 v93, v4, v60
	v_fmac_f32_e32 v93, v6, v62
	v_fmac_f32_e32 v93, v7, v63
	v_add_f32_e32 v91, v91, v93
	v_mul_f32_e32 v93, v9, v65
	v_fmac_f32_e32 v93, v8, v64
	v_fmac_f32_e32 v93, v10, v66
	v_fmac_f32_e32 v93, v11, v67
	v_add_f32_e32 v91, v91, v93
	v_mul_f32_e32 v93, v13, v69
	v_fmac_f32_e32 v93, v12, v68
	v_fmac_f32_e32 v93, v14, v70
	v_fmac_f32_e32 v93, v15, v71
	v_add_f32_e32 v91, v91, v93
	v_mul_f32_e32 v92, v1, v73
	v_fmac_f32_e32 v92, v0, v72
	v_fmac_f32_e32 v92, v2, v74
	v_fmac_f32_e32 v92, v3, v75
	v_mul_f32_e32 v93, v5, v77
	v_fmac_f32_e32 v93, v4, v76
	v_fmac_f32_e32 v93, v6, v78
	v_fmac_f32_e32 v93, v7, v79
	v_add_f32_e32 v92, v92, v93
	v_mul_f32_e32 v93, v9, v81
	v_fmac_f32_e32 v93, v8, v80
	v_fmac_f32_e32 v93, v10, v82
	v_fmac_f32_e32 v93, v11, v83
	v_add_f32_e32 v92, v92, v93
	v_mul_f32_e32 v93, v13, v85
	v_fmac_f32_e32 v93, v12, v84
	v_fmac_f32_e32 v93, v14, v86
	v_fmac_f32_e32 v93, v15, v87
	v_add_f32_e32 v92, v92, v93
	v_add_f32_dpp v89, v89, v89 quad_perm:[1,0,3,2] row_mask:0xf bank_mask:0xf
	v_add_f32_dpp v90, v90, v90 quad_perm:[1,0,3,2] row_mask:0xf bank_mask:0xf
	v_add_f32_dpp v91, v91, v91 quad_perm:[1,0,3,2] row_mask:0xf bank_mask:0xf
	v_add_f32_dpp v92, v92, v92 quad_perm:[1,0,3,2] row_mask:0xf bank_mask:0xf
	v_add_f32_dpp v89, v89, v89 quad_perm:[2,3,0,1] row_mask:0xf bank_mask:0xf
	v_add_f32_dpp v90, v90, v90 quad_perm:[2,3,0,1] row_mask:0xf bank_mask:0xf
	v_add_f32_dpp v91, v91, v91 quad_perm:[2,3,0,1] row_mask:0xf bank_mask:0xf
	v_add_f32_dpp v92, v92, v92 quad_perm:[2,3,0,1] row_mask:0xf bank_mask:0xf
	v_add_f32_dpp v89, v89, v89 row_half_mirror row_mask:0xf bank_mask:0xf
	v_add_f32_dpp v90, v90, v90 row_half_mirror row_mask:0xf bank_mask:0xf
	v_add_f32_dpp v91, v91, v91 row_half_mirror row_mask:0xf bank_mask:0xf
	v_add_f32_dpp v92, v92, v92 row_half_mirror row_mask:0xf bank_mask:0xf
	v_add_f32_dpp v89, v89, v89 row_mirror row_mask:0xf bank_mask:0xf
	v_add_f32_dpp v90, v90, v90 row_mirror row_mask:0xf bank_mask:0xf
	v_add_f32_dpp v91, v91, v91 row_mirror row_mask:0xf bank_mask:0xf
	v_add_f32_dpp v92, v92, v92 row_mirror row_mask:0xf bank_mask:0xf
	v_mul_f32_e32 v89, 0x3d800000, v89
	v_mul_f32_e32 v90, 0x3d800000, v90
	v_mul_f32_e32 v91, 0x3d800000, v91
	v_mul_f32_e32 v92, 0x3d800000, v92
	s_and_saveexec_b64 s[28:29], s[0:1]
	ds_write_b32 v88, v89 offset:80
	ds_write_b32 v88, v90 offset:1104
	ds_write_b32 v88, v91 offset:2128
	ds_write_b32 v88, v92 offset:3152
	s_mov_b64 exec, s[28:29]
	s_waitcnt vmcnt(4)
	v_mul_f32_e32 v89, v97, v25
	v_fmac_f32_e32 v89, v96, v24
	v_fmac_f32_e32 v89, v98, v26
	v_fmac_f32_e32 v89, v99, v27
	v_mul_f32_e32 v93, v101, v29
	v_fmac_f32_e32 v93, v100, v28
	v_fmac_f32_e32 v93, v102, v30
	v_fmac_f32_e32 v93, v103, v31
	v_add_f32_e32 v89, v89, v93
	v_mul_f32_e32 v93, v105, v33
	v_fmac_f32_e32 v93, v104, v32
	v_fmac_f32_e32 v93, v106, v34
	v_fmac_f32_e32 v93, v107, v35
	v_add_f32_e32 v89, v89, v93
	v_mul_f32_e32 v93, v109, v37
	v_fmac_f32_e32 v93, v108, v36
	v_fmac_f32_e32 v93, v110, v38
	v_fmac_f32_e32 v93, v111, v39
	v_add_f32_e32 v89, v89, v93
	v_mul_f32_e32 v90, v97, v41
	v_fmac_f32_e32 v90, v96, v40
	v_fmac_f32_e32 v90, v98, v42
	v_fmac_f32_e32 v90, v99, v43
	v_mul_f32_e32 v93, v101, v45
	v_fmac_f32_e32 v93, v100, v44
	v_fmac_f32_e32 v93, v102, v46
	v_fmac_f32_e32 v93, v103, v47
	v_add_f32_e32 v90, v90, v93
	v_mul_f32_e32 v93, v105, v49
	v_fmac_f32_e32 v93, v104, v48
	v_fmac_f32_e32 v93, v106, v50
	v_fmac_f32_e32 v93, v107, v51
	v_add_f32_e32 v90, v90, v93
	v_mul_f32_e32 v93, v109, v53
	v_fmac_f32_e32 v93, v108, v52
	v_fmac_f32_e32 v93, v110, v54
	v_fmac_f32_e32 v93, v111, v55
	v_add_f32_e32 v90, v90, v93
	v_mul_f32_e32 v91, v97, v57
	v_fmac_f32_e32 v91, v96, v56
	v_fmac_f32_e32 v91, v98, v58
	v_fmac_f32_e32 v91, v99, v59
	v_mul_f32_e32 v93, v101, v61
	v_fmac_f32_e32 v93, v100, v60
	v_fmac_f32_e32 v93, v102, v62
	v_fmac_f32_e32 v93, v103, v63
	v_add_f32_e32 v91, v91, v93
	v_mul_f32_e32 v93, v105, v65
	v_fmac_f32_e32 v93, v104, v64
	v_fmac_f32_e32 v93, v106, v66
	v_fmac_f32_e32 v93, v107, v67
	v_add_f32_e32 v91, v91, v93
	v_mul_f32_e32 v93, v109, v69
	v_fmac_f32_e32 v93, v108, v68
	v_fmac_f32_e32 v93, v110, v70
	v_fmac_f32_e32 v93, v111, v71
	v_add_f32_e32 v91, v91, v93
	v_mul_f32_e32 v92, v97, v73
	v_fmac_f32_e32 v92, v96, v72
	v_fmac_f32_e32 v92, v98, v74
	v_fmac_f32_e32 v92, v99, v75
	v_mul_f32_e32 v93, v101, v77
	v_fmac_f32_e32 v93, v100, v76
	v_fmac_f32_e32 v93, v102, v78
	v_fmac_f32_e32 v93, v103, v79
	v_add_f32_e32 v92, v92, v93
	v_mul_f32_e32 v93, v105, v81
	v_fmac_f32_e32 v93, v104, v80
	v_fmac_f32_e32 v93, v106, v82
	v_fmac_f32_e32 v93, v107, v83
	v_add_f32_e32 v92, v92, v93
	v_mul_f32_e32 v93, v109, v85
	v_fmac_f32_e32 v93, v108, v84
	v_fmac_f32_e32 v93, v110, v86
	v_fmac_f32_e32 v93, v111, v87
	v_add_f32_e32 v92, v92, v93
	v_add_f32_dpp v89, v89, v89 quad_perm:[1,0,3,2] row_mask:0xf bank_mask:0xf
	v_add_f32_dpp v90, v90, v90 quad_perm:[1,0,3,2] row_mask:0xf bank_mask:0xf
	v_add_f32_dpp v91, v91, v91 quad_perm:[1,0,3,2] row_mask:0xf bank_mask:0xf
	v_add_f32_dpp v92, v92, v92 quad_perm:[1,0,3,2] row_mask:0xf bank_mask:0xf
	v_add_f32_dpp v89, v89, v89 quad_perm:[2,3,0,1] row_mask:0xf bank_mask:0xf
	v_add_f32_dpp v90, v90, v90 quad_perm:[2,3,0,1] row_mask:0xf bank_mask:0xf
	v_add_f32_dpp v91, v91, v91 quad_perm:[2,3,0,1] row_mask:0xf bank_mask:0xf
	v_add_f32_dpp v92, v92, v92 quad_perm:[2,3,0,1] row_mask:0xf bank_mask:0xf
	v_add_f32_dpp v89, v89, v89 row_half_mirror row_mask:0xf bank_mask:0xf
	v_add_f32_dpp v90, v90, v90 row_half_mirror row_mask:0xf bank_mask:0xf
	v_add_f32_dpp v91, v91, v91 row_half_mirror row_mask:0xf bank_mask:0xf
	v_add_f32_dpp v92, v92, v92 row_half_mirror row_mask:0xf bank_mask:0xf
	v_add_f32_dpp v89, v89, v89 row_mirror row_mask:0xf bank_mask:0xf
	v_add_f32_dpp v90, v90, v90 row_mirror row_mask:0xf bank_mask:0xf
	v_add_f32_dpp v91, v91, v91 row_mirror row_mask:0xf bank_mask:0xf
	v_add_f32_dpp v92, v92, v92 row_mirror row_mask:0xf bank_mask:0xf
	v_mul_f32_e32 v89, 0x3d800000, v89
	v_mul_f32_e32 v90, 0x3d800000, v90
	v_mul_f32_e32 v91, 0x3d800000, v91
	v_mul_f32_e32 v92, 0x3d800000, v92
	s_and_saveexec_b64 s[28:29], s[0:1]
	ds_write_b32 v88, v89 offset:96
	ds_write_b32 v88, v90 offset:1120
	ds_write_b32 v88, v91 offset:2144
	ds_write_b32 v88, v92 offset:3168
	s_mov_b64 exec, s[28:29]
	s_waitcnt vmcnt(0)
	v_mul_f32_e32 v89, v113, v25
	v_fmac_f32_e32 v89, v112, v24
	v_fmac_f32_e32 v89, v114, v26
	v_fmac_f32_e32 v89, v115, v27
	v_mul_f32_e32 v93, v117, v29
	v_fmac_f32_e32 v93, v116, v28
	v_fmac_f32_e32 v93, v118, v30
	v_fmac_f32_e32 v93, v119, v31
	v_add_f32_e32 v89, v89, v93
	v_mul_f32_e32 v93, v121, v33
	v_fmac_f32_e32 v93, v120, v32
	v_fmac_f32_e32 v93, v122, v34
	v_fmac_f32_e32 v93, v123, v35
	v_add_f32_e32 v89, v89, v93
	v_mul_f32_e32 v93, v125, v37
	v_fmac_f32_e32 v93, v124, v36
	v_fmac_f32_e32 v93, v126, v38
	v_fmac_f32_e32 v93, v127, v39
	v_add_f32_e32 v89, v89, v93
	v_mul_f32_e32 v90, v113, v41
	v_fmac_f32_e32 v90, v112, v40
	v_fmac_f32_e32 v90, v114, v42
	v_fmac_f32_e32 v90, v115, v43
	v_mul_f32_e32 v93, v117, v45
	v_fmac_f32_e32 v93, v116, v44
	v_fmac_f32_e32 v93, v118, v46
	v_fmac_f32_e32 v93, v119, v47
	v_add_f32_e32 v90, v90, v93
	v_mul_f32_e32 v93, v121, v49
	v_fmac_f32_e32 v93, v120, v48
	v_fmac_f32_e32 v93, v122, v50
	v_fmac_f32_e32 v93, v123, v51
	v_add_f32_e32 v90, v90, v93
	v_mul_f32_e32 v93, v125, v53
	v_fmac_f32_e32 v93, v124, v52
	v_fmac_f32_e32 v93, v126, v54
	v_fmac_f32_e32 v93, v127, v55
	v_add_f32_e32 v90, v90, v93
	v_mul_f32_e32 v91, v113, v57
	v_fmac_f32_e32 v91, v112, v56
	v_fmac_f32_e32 v91, v114, v58
	v_fmac_f32_e32 v91, v115, v59
	v_mul_f32_e32 v93, v117, v61
	v_fmac_f32_e32 v93, v116, v60
	v_fmac_f32_e32 v93, v118, v62
	v_fmac_f32_e32 v93, v119, v63
	v_add_f32_e32 v91, v91, v93
	v_mul_f32_e32 v93, v121, v65
	v_fmac_f32_e32 v93, v120, v64
	v_fmac_f32_e32 v93, v122, v66
	v_fmac_f32_e32 v93, v123, v67
	v_add_f32_e32 v91, v91, v93
	v_mul_f32_e32 v93, v125, v69
	v_fmac_f32_e32 v93, v124, v68
	v_fmac_f32_e32 v93, v126, v70
	v_fmac_f32_e32 v93, v127, v71
	v_add_f32_e32 v91, v91, v93
	v_mul_f32_e32 v92, v113, v73
	v_fmac_f32_e32 v92, v112, v72
	v_fmac_f32_e32 v92, v114, v74
	v_fmac_f32_e32 v92, v115, v75
	v_mul_f32_e32 v93, v117, v77
	v_fmac_f32_e32 v93, v116, v76
	v_fmac_f32_e32 v93, v118, v78
	v_fmac_f32_e32 v93, v119, v79
	v_add_f32_e32 v92, v92, v93
	v_mul_f32_e32 v93, v121, v81
	v_fmac_f32_e32 v93, v120, v80
	v_fmac_f32_e32 v93, v122, v82
	v_fmac_f32_e32 v93, v123, v83
	v_add_f32_e32 v92, v92, v93
	v_mul_f32_e32 v93, v125, v85
	v_fmac_f32_e32 v93, v124, v84
	v_fmac_f32_e32 v93, v126, v86
	v_fmac_f32_e32 v93, v127, v87
	v_add_f32_e32 v92, v92, v93
	v_add_f32_dpp v89, v89, v89 quad_perm:[1,0,3,2] row_mask:0xf bank_mask:0xf
	v_add_f32_dpp v90, v90, v90 quad_perm:[1,0,3,2] row_mask:0xf bank_mask:0xf
	v_add_f32_dpp v91, v91, v91 quad_perm:[1,0,3,2] row_mask:0xf bank_mask:0xf
	v_add_f32_dpp v92, v92, v92 quad_perm:[1,0,3,2] row_mask:0xf bank_mask:0xf
	v_add_f32_dpp v89, v89, v89 quad_perm:[2,3,0,1] row_mask:0xf bank_mask:0xf
	v_add_f32_dpp v90, v90, v90 quad_perm:[2,3,0,1] row_mask:0xf bank_mask:0xf
	v_add_f32_dpp v91, v91, v91 quad_perm:[2,3,0,1] row_mask:0xf bank_mask:0xf
	v_add_f32_dpp v92, v92, v92 quad_perm:[2,3,0,1] row_mask:0xf bank_mask:0xf
	v_add_f32_dpp v89, v89, v89 row_half_mirror row_mask:0xf bank_mask:0xf
	v_add_f32_dpp v90, v90, v90 row_half_mirror row_mask:0xf bank_mask:0xf
	v_add_f32_dpp v91, v91, v91 row_half_mirror row_mask:0xf bank_mask:0xf
	v_add_f32_dpp v92, v92, v92 row_half_mirror row_mask:0xf bank_mask:0xf
	v_add_f32_dpp v89, v89, v89 row_mirror row_mask:0xf bank_mask:0xf
	v_add_f32_dpp v90, v90, v90 row_mirror row_mask:0xf bank_mask:0xf
	v_add_f32_dpp v91, v91, v91 row_mirror row_mask:0xf bank_mask:0xf
	v_add_f32_dpp v92, v92, v92 row_mirror row_mask:0xf bank_mask:0xf
	v_mul_f32_e32 v89, 0x3d800000, v89
	v_mul_f32_e32 v90, 0x3d800000, v90
	v_mul_f32_e32 v91, 0x3d800000, v91
	v_mul_f32_e32 v92, 0x3d800000, v92
	s_and_saveexec_b64 s[28:29], s[0:1]
	ds_write_b32 v88, v89 offset:112
	ds_write_b32 v88, v90 offset:1136
	ds_write_b32 v88, v91 offset:2160
	ds_write_b32 v88, v92 offset:3184
	s_mov_b64 exec, s[28:29]
